# attention queue: first unit of each workgroup is its block id (no ticket burst), later tickets offset by grid size; h0 with all 8 items in flight; A-unit epilogue gain/lambda loads hoisted
# baseline (speedup 1.0000x reference)
.LBB0_16:
	s_or_b64 exec, exec, s[2:3]
	v_writelane_b32 v255, s72, 42
	s_cmpk_lt_i32 s90, 0xc0
	s_cselect_b64 s[2:3], -1, 0
	s_cmpk_gt_i32 s90, 0xbf
	s_mov_b64 s[4:5], -1
	s_cbranch_scc0 .LBB0_29
	s_cmpk_lg_i32 s90, 0xc0
	s_cbranch_scc1 .LBB0_52
	s_mov_b32 s5, s91
	s_mov_b32 s4, 0
	s_nop 0
	v_or_b32_e32 v0, s5, v230
	s_movk_i32 s5, 0x400
	v_cmp_gt_i32_e32 vcc, s5, v0
	s_and_saveexec_b64 s[12:13], vcc
	s_cbranch_execz .LBB0_51
	v_and_b32_e32 v1, 15, v0
	v_cvt_f32_ubyte0_e32 v1, v1
	v_mul_f32_e32 v2, 0xbf549a78, v1
	s_mov_b32 s6, 0xc2fc0000
	v_mov_b32_e32 v3, 0x42800000
	v_cmp_gt_f32_e32 vcc, s6, v2
	v_not_b32_e32 v6, 63
	s_mov_b32 s5, 0
	v_cndmask_b32_e32 v2, 0, v3, vcc
	v_fmac_f32_e32 v2, 0xbf549a78, v1
	v_exp_f32_e32 v1, v2
	v_cndmask_b32_e32 v2, 0, v6, vcc
	s_xor_b64 s[4:5], s[4:5], s[48:49]
	s_mov_b64 s[14:15], 0
	v_ldexp_f32 v7, v1, v2
	v_ashrrev_i32_e32 v1, 31, v0
	v_lshl_add_u64 v[2:3], v[0:1], 2, s[4:5]
	s_mov_b64 s[4:5], 0x4a3d000
	v_lshl_add_u64 v[2:3], v[2:3], 0, s[4:5]
	s_brev_b32 s20, 18
	s_mov_b32 s21, 0xfe5163ab
	v_mov_b32_e32 v5, 0
	s_mov_b32 s22, 0x3c439041
	s_mov_b32 s23, 0xdb629599
	s_mov_b32 s24, 0xf534ddc0
	s_mov_b32 s25, 0xfc2757d1
	s_mov_b32 s26, 0x4e441529
	s_mov_b32 s27, 0xa2f9836e
	s_mov_b32 s28, 0x3fc90fda
	s_mov_b32 s29, 0x3f22f983
	s_mov_b32 s30, 0xbfc90fda
	v_mov_b32_e32 v1, 0x3c0881c4
	v_mov_b32_e32 v8, 0xbab64f3b
	s_brev_b32 s31, 1
	s_movk_i32 s34, 0x1f8
	s_mov_b64 s[16:17], 0x800
	s_movk_i32 s35, 0x1ff
	v_not_b32_e32 v9, 31
	v_mov_b32_e32 v10, 0x7fc00000
	s_branch .LBB0_21

.LBB0_138:
	s_or_b64 exec, exec, s[2:3]
	s_mov_b32 s2, s91
	s_waitcnt lgkmcnt(0)
	s_barrier
	s_cmp_lg_u32 s72, 0x100
	s_cbranch_scc1 .Lh0_generic
	v_readlane_b32 s4, v251, 0
	v_readlane_b32 s5, v251, 1
	v_mov_b32_e32 v1, 0
	v_or_b32_e32 v2, s91, v230
	s_nop 2
	s_load_dwordx4 s[8:11], s[4:5], 0x0
	s_add_u32 s6, s48, 0x4a00000
	s_addc_u32 s7, s49, 0
	s_add_u32 s14, s6, 0x1000
	s_addc_u32 s15, s7, 0
	s_add_u32 s12, s48, 0x4a3e000
	s_addc_u32 s13, s49, 0
	s_lshl_b32 s0, s90, 2
	v_lshrrev_b32_e32 v0, 7, v2
	v_add_u32_e32 v0, s0, v0
	v_and_b32_e32 v36, 0x7f, v2
	v_lshlrev_b32_e32 v3, 12, v0
	v_lshl_or_b32 v3, v36, 5, v3
	v_add_u32_e32 v4, 0x400000, v3
	v_add_u32_e32 v5, 0x800000, v3
	v_add_u32_e32 v6, 0xc00000, v3
	v_lshlrev_b32_e32 v7, 5, v36
	v_add_u32_e32 v8, 0x6000, v7
	v_add_u32_e32 v9, 0xc000, v7
	v_add_u32_e32 v10, 0x12000, v7
	v_add_u32_e32 v11, 0x18000, v7
	v_lshlrev_b32_e32 v12, 11, v0
	v_lshl_or_b32 v12, v36, 4, v12
	v_add_u32_e32 v13, 0x200000, v12
	v_add_u32_e32 v14, 0x400000, v12
	v_add_u32_e32 v15, 0x600000, v12
	v_add_u32_e32 v16, 0x800000, v12
	v_add_u32_e32 v17, 0xa00000, v12
	v_add_u32_e32 v18, 0xc00000, v12
	v_add_u32_e32 v19, 0xe00000, v12
	s_waitcnt lgkmcnt(0)
	global_load_dwordx4 v[120:123], v7, s[6:7]
	global_load_dwordx4 v[124:127], v7, s[6:7] offset:16
	global_load_dwordx4 v[128:131], v7, s[14:15]
	global_load_dwordx4 v[132:135], v7, s[14:15] offset:16
	global_load_dwordx4 v[50:53], v3, s[8:9]
	global_load_dwordx4 v[54:57], v3, s[8:9] offset:16
	global_load_dwordx4 v[58:61], v4, s[8:9]
	global_load_dwordx4 v[62:65], v4, s[8:9] offset:16
	global_load_dwordx4 v[66:69], v5, s[8:9]
	global_load_dwordx4 v[70:73], v5, s[8:9] offset:16
	global_load_dwordx4 v[74:77], v6, s[8:9]
	global_load_dwordx4 v[78:81], v6, s[8:9] offset:16
	global_load_dwordx4 v[136:139], v8, s[6:7]
	global_load_dwordx4 v[140:143], v8, s[6:7] offset:16
	global_load_dwordx4 v[144:147], v8, s[14:15]
	global_load_dwordx4 v[148:151], v8, s[14:15] offset:16
	global_load_dwordx4 v[82:85], v3, s[10:11]
	global_load_dwordx4 v[86:89], v3, s[10:11] offset:16
	global_load_dwordx4 v[152:155], v9, s[6:7]
	global_load_dwordx4 v[156:159], v9, s[6:7] offset:16
	global_load_dwordx4 v[160:163], v9, s[14:15]
	global_load_dwordx4 v[164:167], v9, s[14:15] offset:16
	global_load_dwordx4 v[90:93], v4, s[10:11]
	global_load_dwordx4 v[94:97], v4, s[10:11] offset:16
	global_load_dwordx4 v[168:171], v10, s[6:7]
	global_load_dwordx4 v[172:175], v10, s[6:7] offset:16
	global_load_dwordx4 v[176:179], v10, s[14:15]
	global_load_dwordx4 v[180:183], v10, s[14:15] offset:16
	global_load_dwordx4 v[98:101], v5, s[10:11]
	global_load_dwordx4 v[102:105], v5, s[10:11] offset:16
	global_load_dwordx4 v[184:187], v11, s[6:7]
	global_load_dwordx4 v[188:191], v11, s[6:7] offset:16
	global_load_dwordx4 v[192:195], v11, s[14:15]
	global_load_dwordx4 v[196:199], v11, s[14:15] offset:16
	global_load_dwordx4 v[106:109], v6, s[10:11]
	global_load_dwordx4 v[110:113], v6, s[10:11] offset:16
	s_waitcnt vmcnt(30)
	v_pk_add_f32 v[128:129], v[128:129], 1.0 op_sel_hi:[1,0]
	v_pk_add_f32 v[130:131], v[130:131], 1.0 op_sel_hi:[1,0]
	v_pk_add_f32 v[132:133], v[132:133], 1.0 op_sel_hi:[1,0]
	v_pk_add_f32 v[134:135], v[134:135], 1.0 op_sel_hi:[1,0]
	v_pk_fma_f32 v[20:21], v[50:51], v[128:129], v[120:121]
	v_pk_fma_f32 v[22:23], v[52:53], v[130:131], v[122:123]
	v_pk_fma_f32 v[24:25], v[54:55], v[132:133], v[124:125]
	v_pk_fma_f32 v[26:27], v[56:57], v[134:135], v[126:127]
	v_cvt_pk_bf16_f32 v28, v20, v21
	v_cvt_pk_bf16_f32 v29, v22, v23
	v_cvt_pk_bf16_f32 v30, v24, v25
	v_cvt_pk_bf16_f32 v31, v26, v27
	global_store_dwordx4 v12, v[28:31], s[12:13]
	s_waitcnt vmcnt(29)
	v_pk_fma_f32 v[20:21], v[58:59], v[128:129], v[120:121]
	v_pk_fma_f32 v[22:23], v[60:61], v[130:131], v[122:123]
	v_pk_fma_f32 v[24:25], v[62:63], v[132:133], v[124:125]
	v_pk_fma_f32 v[26:27], v[64:65], v[134:135], v[126:127]
	v_cvt_pk_bf16_f32 v32, v20, v21
	v_cvt_pk_bf16_f32 v33, v22, v23
	v_cvt_pk_bf16_f32 v34, v24, v25
	v_cvt_pk_bf16_f32 v35, v26, v27
	global_store_dwordx4 v13, v[32:35], s[12:13]
	s_waitcnt vmcnt(28)
	v_pk_fma_f32 v[20:21], v[66:67], v[128:129], v[120:121]
	v_pk_fma_f32 v[22:23], v[68:69], v[130:131], v[122:123]
	v_pk_fma_f32 v[24:25], v[70:71], v[132:133], v[124:125]
	v_pk_fma_f32 v[26:27], v[72:73], v[134:135], v[126:127]
	v_cvt_pk_bf16_f32 v28, v20, v21
	v_cvt_pk_bf16_f32 v29, v22, v23
	v_cvt_pk_bf16_f32 v30, v24, v25
	v_cvt_pk_bf16_f32 v31, v26, v27
	global_store_dwordx4 v14, v[28:31], s[12:13]
	s_waitcnt vmcnt(27)
	v_pk_fma_f32 v[20:21], v[74:75], v[128:129], v[120:121]
	v_pk_fma_f32 v[22:23], v[76:77], v[130:131], v[122:123]
	v_pk_fma_f32 v[24:25], v[78:79], v[132:133], v[124:125]
	v_pk_fma_f32 v[26:27], v[80:81], v[134:135], v[126:127]
	v_cvt_pk_bf16_f32 v32, v20, v21
	v_cvt_pk_bf16_f32 v33, v22, v23
	v_cvt_pk_bf16_f32 v34, v24, v25
	v_cvt_pk_bf16_f32 v35, v26, v27
	global_store_dwordx4 v15, v[32:35], s[12:13]
	s_waitcnt vmcnt(22)
	v_pk_add_f32 v[144:145], v[144:145], 1.0 op_sel_hi:[1,0]
	v_pk_add_f32 v[146:147], v[146:147], 1.0 op_sel_hi:[1,0]
	v_pk_add_f32 v[148:149], v[148:149], 1.0 op_sel_hi:[1,0]
	v_pk_add_f32 v[150:151], v[150:151], 1.0 op_sel_hi:[1,0]
	v_pk_fma_f32 v[20:21], v[82:83], v[144:145], v[136:137]
	v_pk_fma_f32 v[22:23], v[84:85], v[146:147], v[138:139]
	v_pk_fma_f32 v[24:25], v[86:87], v[148:149], v[140:141]
	v_pk_fma_f32 v[26:27], v[88:89], v[150:151], v[142:143]
	v_cvt_pk_bf16_f32 v28, v20, v21
	v_cvt_pk_bf16_f32 v29, v22, v23
	v_cvt_pk_bf16_f32 v30, v24, v25
	v_cvt_pk_bf16_f32 v31, v26, v27
	global_store_dwordx4 v16, v[28:31], s[12:13]
	s_waitcnt vmcnt(17)
	v_pk_add_f32 v[160:161], v[160:161], 1.0 op_sel_hi:[1,0]
	v_pk_add_f32 v[162:163], v[162:163], 1.0 op_sel_hi:[1,0]
	v_pk_add_f32 v[164:165], v[164:165], 1.0 op_sel_hi:[1,0]
	v_pk_add_f32 v[166:167], v[166:167], 1.0 op_sel_hi:[1,0]
	v_pk_fma_f32 v[20:21], v[90:91], v[160:161], v[152:153]
	v_pk_fma_f32 v[22:23], v[92:93], v[162:163], v[154:155]
	v_pk_fma_f32 v[24:25], v[94:95], v[164:165], v[156:157]
	v_pk_fma_f32 v[26:27], v[96:97], v[166:167], v[158:159]
	v_cvt_pk_bf16_f32 v32, v20, v21
	v_cvt_pk_bf16_f32 v33, v22, v23
	v_cvt_pk_bf16_f32 v34, v24, v25
	v_cvt_pk_bf16_f32 v35, v26, v27
	global_store_dwordx4 v17, v[32:35], s[12:13]
	s_waitcnt vmcnt(12)
	v_pk_add_f32 v[176:177], v[176:177], 1.0 op_sel_hi:[1,0]
	v_pk_add_f32 v[178:179], v[178:179], 1.0 op_sel_hi:[1,0]
	v_pk_add_f32 v[180:181], v[180:181], 1.0 op_sel_hi:[1,0]
	v_pk_add_f32 v[182:183], v[182:183], 1.0 op_sel_hi:[1,0]
	v_pk_fma_f32 v[20:21], v[98:99], v[176:177], v[168:169]
	v_pk_fma_f32 v[22:23], v[100:101], v[178:179], v[170:171]
	v_pk_fma_f32 v[24:25], v[102:103], v[180:181], v[172:173]
	v_pk_fma_f32 v[26:27], v[104:105], v[182:183], v[174:175]
	v_cvt_pk_bf16_f32 v28, v20, v21
	v_cvt_pk_bf16_f32 v29, v22, v23
	v_cvt_pk_bf16_f32 v30, v24, v25
	v_cvt_pk_bf16_f32 v31, v26, v27
	global_store_dwordx4 v18, v[28:31], s[12:13]
	s_waitcnt vmcnt(7)
	v_pk_add_f32 v[192:193], v[192:193], 1.0 op_sel_hi:[1,0]
	v_pk_add_f32 v[194:195], v[194:195], 1.0 op_sel_hi:[1,0]
	v_pk_add_f32 v[196:197], v[196:197], 1.0 op_sel_hi:[1,0]
	v_pk_add_f32 v[198:199], v[198:199], 1.0 op_sel_hi:[1,0]
	v_pk_fma_f32 v[20:21], v[106:107], v[192:193], v[184:185]
	v_pk_fma_f32 v[22:23], v[108:109], v[194:195], v[186:187]
	v_pk_fma_f32 v[24:25], v[110:111], v[196:197], v[188:189]
	v_pk_fma_f32 v[26:27], v[112:113], v[198:199], v[190:191]
	v_cvt_pk_bf16_f32 v32, v20, v21
	v_cvt_pk_bf16_f32 v33, v22, v23
	v_cvt_pk_bf16_f32 v34, v24, v25
	v_cvt_pk_bf16_f32 v35, v26, v27
	global_store_dwordx4 v19, v[32:35], s[12:13]
	s_mov_b64 s[2:3], exec
	s_branch .LBB0_145
.Lh0_generic:
	s_mov_b32 s4, 0
	s_mov_b32 s8, 0
	s_nop 0
	v_or_b32_e32 v0, s2, v230
	v_lshl_add_u32 v6, s90, 9, v0
	s_mov_b32 s2, 0x100000
	v_cmp_gt_i32_e32 vcc, s2, v6
	s_and_saveexec_b64 s[2:3], vcc
	s_cbranch_execz .LBB0_145
	s_mov_b32 s5, 0
	s_xor_b64 s[6:7], s[4:5], s[48:49]
	v_readlane_b32 s0, v251, 0
	s_add_u32 s6, s6, 0x4a00000
	s_mov_b32 s9, s5
	v_readlane_b32 s1, v251, 1
	s_addc_u32 s7, s7, 0
	s_xor_b64 s[4:5], s[8:9], s[48:49]
	s_load_dwordx4 s[8:11], s[0:1], 0x0
	s_add_u32 s12, s4, 0x4a3e000
	v_lshlrev_b32_e32 v0, 3, v0
	s_addc_u32 s13, s5, 0
	s_lshl_b32 s18, s72, 9
	v_lshl_add_u32 v7, s90, 12, v0
	s_lshl_b32 s19, s72, 12
	s_mov_b64 s[14:15], 0
	s_movk_i32 s20, 0x1000
	s_movk_i32 s21, 0xfff
	v_mov_b32_e32 v1, 0
	s_movk_i32 s22, 0x1800
	s_mov_b64 s[16:17], 0x1000
	s_mov_b32 s23, 0xfffff
	s_branch .LBB0_141

.LBB0_358:
	s_or_b64 exec, exec, s[0:1]
	v_readlane_b32 s0, v254, 16
	v_readlane_b32 s1, v254, 17
	s_xor_b64 s[0:1], s[0:1], -1
	v_writelane_b32 v254, s0, 55
	s_waitcnt lgkmcnt(0)
	s_barrier
	v_writelane_b32 v254, s1, 56
	s_nop 0
	v_readlane_b32 s20, v254, 53
	v_readlane_b32 s21, v254, 54
	s_mov_b32 s64, 0
	s_xor_b64 s[0:1], s[64:65], s[62:63]
	s_lshl_b64 s[2:3], s[20:21], 2
	s_add_u32 s0, s0, s2
	s_addc_u32 s1, s1, s3
	s_add_u32 s0, s0, 0xee3e000
	s_addc_u32 s1, s1, 0
	v_writelane_b32 v254, s0, 57
	s_lshl_b32 s64, s20, 7
	v_readlane_b32 s4, v251, 62
	v_writelane_b32 v254, s1, 58
	s_mul_i32 s0, s20, 20
	v_writelane_b32 v254, s0, 59
	s_lshl_b64 s[0:1], s[64:65], 2
	v_readlane_b32 s14, v252, 8
	v_readlane_b32 s5, v251, 63
	v_readlane_b32 s15, v252, 9
	s_add_u32 s4, s14, s0
	s_addc_u32 s5, s15, s1
	v_writelane_b32 v254, s4, 60
	v_readlane_b32 s10, v252, 4
	v_readlane_b32 s6, v252, 0
	v_writelane_b32 v254, s5, 61
	s_lshl_b32 s4, s20, 3
	v_writelane_b32 v254, s4, 62
	s_lshl_b32 s4, s20, 8
	s_mov_b32 s5, s65
	s_mov_b32 s10, s4
	s_lshl_b64 s[4:5], s[4:5], 2
	v_readlane_b32 s7, v252, 1
	v_readlane_b32 s11, v252, 5
	s_add_u32 s4, s6, s4
	v_writelane_b32 v254, s10, 63
	s_addc_u32 s5, s7, s5
	v_readlane_b32 s8, v252, 2
	v_writelane_b32 v255, s11, 0
	v_writelane_b32 v255, s4, 1
	v_readlane_b32 s9, v252, 3
	v_readlane_b32 s12, v252, 6
	v_writelane_b32 v255, s5, 2
	v_readlane_b32 s4, v251, 0
	v_readlane_b32 s5, v251, 1
	s_add_u32 s2, s4, s2
	s_addc_u32 s3, s5, s3
	v_writelane_b32 v255, s2, 3
	s_add_u32 s0, s8, s0
	s_addc_u32 s1, s9, s1
	v_writelane_b32 v255, s3, 4
	v_readlane_b32 s13, v252, 7
	v_readlane_b32 s16, v252, 10
	v_readlane_b32 s17, v252, 11
	v_readlane_b32 s18, v252, 12
	v_readlane_b32 s19, v252, 13
	v_writelane_b32 v255, s0, 5
	s_mov_b32 s37, s65
	v_readlane_b32 s4, v251, 44
	v_writelane_b32 v255, s1, 6
	s_lshl_b32 s0, s20, 1
	v_writelane_b32 v255, s0, 7
	s_lshl_b64 s[0:1], s[36:37], 2
	v_readlane_b32 s8, v251, 48
	v_readlane_b32 s9, v251, 49
	s_add_u32 s0, s8, s0
	v_writelane_b32 v255, s0, 8
	s_addc_u32 s0, s9, s1
	v_writelane_b32 v255, s0, 9
	v_readlane_b32 s5, v251, 45
	v_readlane_b32 s6, v251, 46
	v_readlane_b32 s7, v251, 47
	v_readlane_b32 s10, v251, 50
	v_readlane_b32 s11, v251, 51
	v_readlane_b32 s12, v251, 52
	v_readlane_b32 s13, v251, 53
	v_readlane_b32 s14, v251, 54
	v_readlane_b32 s15, v251, 55
	v_readlane_b32 s16, v251, 56
	v_readlane_b32 s17, v251, 57
	v_readlane_b32 s18, v251, 58
	v_readlane_b32 s19, v251, 59
	s_mov_b32 s0, 1
	v_writelane_b32 v255, s0, 41
	s_branch .LBB0_362

.LBB0_362:
	s_mov_b32 s0, s91
	s_barrier
	s_nop 0
	v_or_b32_e32 v0, s0, v230
	v_cmp_eq_u32_e32 vcc, 0, v0
	s_and_saveexec_b64 s[0:1], vcc
	s_cbranch_execz .LBB0_364
	v_readlane_b32 s2, v255, 41
	s_nop 3
	s_cmp_eq_u32 s2, 0
	s_cbranch_scc1 .Lq_dyn
	s_mov_b32 s2, 0
	v_writelane_b32 v255, s2, 41
	v_readlane_b32 s2, v254, 32
	s_nop 3
	v_mov_b32_e32 v0, s2
	s_branch .Lq_have
.Lq_dyn:
	v_readlane_b32 s2, v254, 57
	v_readlane_b32 s3, v254, 58
	s_nop 1
	v_mov_b64_e32 v[2:3], s[2:3]
	flat_atomic_add v0, v[2:3], v237 sc0
	s_waitcnt vmcnt(0) lgkmcnt(0)
	v_readlane_b32 s3, v255, 42
	s_nop 1
	v_add_u32_e32 v0, s3, v0
.Lq_have:
	v_readlane_b32 s2, v254, 15
	s_nop 1
	v_mov_b32_e32 v2, s2
	s_waitcnt vmcnt(0) lgkmcnt(0)
	ds_write_b32 v2, v0

.LBB0_455:
	v_readlane_b32 s0, v255, 5
	v_readlane_b32 s1, v255, 6
	v_lshrrev_b32_e32 v202, 2, v165
	v_and_b32_e32 v202, 12, v202
	v_lshlrev_b32_e32 v202, 2, v202
	s_nop 2
	global_load_dwordx4 v[204:207], v202, s[0:1]
	global_load_dwordx4 v[208:211], v202, s[0:1] offset:64
	global_load_dwordx4 v[212:215], v202, s[0:1] offset:128
	global_load_dwordx4 v[216:219], v202, s[0:1] offset:192
	global_load_dwordx4 v[220:223], v202, s[0:1] offset:256
	global_load_dwordx4 v[224:227], v202, s[0:1] offset:320
	global_load_dwordx4 v[116:119], v202, s[0:1] offset:384
	global_load_dwordx4 v[120:123], v202, s[0:1] offset:448
	ds_bpermute_b32 v2, v236, v3
	v_and_b32_e32 v0, 63, v165
	v_readlane_b32 s0, v255, 1
	v_lshlrev_b32_e32 v0, 2, v0
	v_readlane_b32 s1, v255, 2
	s_waitcnt lgkmcnt(0)
	v_add_f32_e32 v2, v3, v2
	ds_bpermute_b32 v3, v231, v2
	s_mov_b32 s2, 0x42b17218
	s_waitcnt lgkmcnt(0)
	v_add_f32_e32 v4, v2, v3
	ds_bpermute_b32 v2, v236, v188
	s_waitcnt lgkmcnt(0)
	v_add_f32_e32 v3, v188, v2
	global_load_dword v2, v0, s[0:1]
	global_load_dword v5, v0, s[0:1] offset:256
	global_load_dword v124, v0, s[0:1] offset:512
	global_load_dword v125, v0, s[0:1] offset:768
	s_waitcnt vmcnt(0)
	ds_bpermute_b32 v21, v231, v3
	v_mul_f32_e32 v6, v2, v5
	ds_bpermute_b32 v6, v231, v6
	s_waitcnt lgkmcnt(0)
	v_fmac_f32_e32 v6, v2, v5
	ds_bpermute_b32 v2, v236, v6
	s_waitcnt lgkmcnt(0)
	v_add_f32_e32 v2, v6, v2
	ds_bpermute_b32 v5, v232, v2
	s_waitcnt lgkmcnt(0)
	v_add_f32_e32 v2, v2, v5
	ds_bpermute_b32 v5, v233, v2
	s_waitcnt lgkmcnt(0)
	v_add_f32_e32 v2, v2, v5
	ds_bpermute_b32 v5, v234, v2
	s_waitcnt lgkmcnt(0)
	v_add_f32_e32 v2, v2, v5
	ds_bpermute_b32 v5, v235, v2
	s_waitcnt lgkmcnt(0)
	v_add_f32_e32 v2, v2, v5
	v_mov_b32_e32 v5, v124
	s_nop 0
	v_mov_b32_e32 v0, v125
	v_readlane_b32 s0, v255, 3
	v_readlane_b32 s1, v255, 4
	s_load_dword s0, s[0:1], 0xf8
	s_mov_b32 s1, 0xc2ce8ed0
	v_cmp_ngt_f32_e32 vcc, s1, v2
	s_mov_b32 s64, 0
	s_waitcnt lgkmcnt(0)
	v_mov_b32_e32 v20, s0
	s_waitcnt vmcnt(0)
	v_mul_f32_e32 v6, v5, v0
	ds_bpermute_b32 v6, v231, v6
	s_waitcnt lgkmcnt(0)
	v_fmac_f32_e32 v6, v5, v0
	ds_bpermute_b32 v0, v236, v6
	s_waitcnt lgkmcnt(0)
	v_add_f32_e32 v0, v6, v0
	ds_bpermute_b32 v5, v232, v0
	s_waitcnt lgkmcnt(0)
	v_add_f32_e32 v0, v0, v5
	ds_bpermute_b32 v5, v233, v0
	s_waitcnt lgkmcnt(0)
	v_add_f32_e32 v0, v0, v5
	ds_bpermute_b32 v5, v234, v0
	s_waitcnt lgkmcnt(0)
	v_add_f32_e32 v0, v0, v5
	ds_bpermute_b32 v5, v235, v0
	s_waitcnt lgkmcnt(0)
	v_add_f32_e32 v0, v0, v5
	v_mul_f32_e32 v5, 0x3fb8aa3b, v2
	v_fma_f32 v6, v2, s33, -v5
	v_rndne_f32_e32 v7, v5
	v_fmac_f32_e32 v6, 0x32a5705f, v2
	v_sub_f32_e32 v5, v5, v7
	v_add_f32_e32 v5, v5, v6
	v_exp_f32_e32 v5, v5
	v_cvt_i32_f32_e32 v6, v7
	v_ldexp_f32 v5, v5, v6
	v_cndmask_b32_e32 v5, 0, v5, vcc
	v_cmp_nlt_f32_e32 vcc, s2, v2
	s_nop 1
	v_cndmask_b32_e32 v2, v243, v5, vcc
	v_mul_f32_e32 v5, 0x3fb8aa3b, v0
	v_fma_f32 v6, v0, s33, -v5
	v_rndne_f32_e32 v7, v5
	v_fmac_f32_e32 v6, 0x32a5705f, v0
	v_sub_f32_e32 v5, v5, v7
	v_add_f32_e32 v5, v5, v6
	v_exp_f32_e32 v5, v5
	v_cvt_i32_f32_e32 v6, v7
	v_cmp_ngt_f32_e32 vcc, s1, v0
	v_ldexp_f32 v5, v5, v6
	s_nop 0
	v_cndmask_b32_e32 v5, 0, v5, vcc
	v_cmp_nlt_f32_e32 vcc, s2, v0
	s_nop 1
	v_cndmask_b32_e32 v0, v243, v5, vcc
	v_sub_f32_e32 v2, v2, v0
	v_div_scale_f32 v0, s[0:1], v4, v4, 1.0
	v_rcp_f32_e32 v5, v0
	v_pk_add_f32 v[2:3], v[20:21], v[2:3]
	v_sub_f32_e32 v20, 1.0, v20
	v_fma_f32 v6, -v0, v5, 1.0
	v_fmac_f32_e32 v5, v6, v5
	v_div_scale_f32 v6, vcc, 1.0, v4, 1.0
	v_mul_f32_e32 v7, v6, v5
	v_fma_f32 v8, -v0, v7, v6
	v_fmac_f32_e32 v7, v8, v5
	v_fma_f32 v0, -v0, v7, v6
	v_div_fmas_f32 v0, v0, v5, v7
	v_div_fixup_f32 v0, v0, v4, 1.0
	v_div_scale_f32 v4, s[0:1], v3, v3, v2
	v_rcp_f32_e32 v5, v4
	s_xor_b64 s[0:1], s[64:65], s[62:63]
	s_lshl_b32 s64, s4, 1
	v_fma_f32 v6, -v4, v5, 1.0
	v_fmac_f32_e32 v5, v6, v5
	v_div_scale_f32 v6, vcc, v2, v3, v2
	v_mul_f32_e32 v7, v6, v5
	v_fma_f32 v8, -v4, v7, v6
	v_fmac_f32_e32 v7, v8, v5
	v_fma_f32 v4, -v4, v7, v6
	v_div_fmas_f32 v4, v4, v5, v7
	v_div_fixup_f32 v2, v4, v3, v2
	v_pk_mul_f32 v[4:5], v[60:61], v[2:3] op_sel_hi:[1,0]
	v_pk_mul_f32 v[6:7], v[62:63], v[2:3] op_sel_hi:[1,0]
	v_pk_fma_f32 v[36:37], v[64:65], v[0:1], v[4:5] op_sel_hi:[1,0,1] neg_lo:[0,0,1] neg_hi:[0,0,1]
	v_pk_fma_f32 v[34:35], v[66:67], v[0:1], v[6:7] op_sel_hi:[1,0,1] neg_lo:[0,0,1] neg_hi:[0,0,1]
	v_mul_f32_e32 v3, v37, v37
	v_fmac_f32_e32 v3, v36, v36
	v_fmac_f32_e32 v3, v34, v34
	v_fmac_f32_e32 v3, v35, v35
	v_pk_mul_f32 v[4:5], v[52:53], v[2:3] op_sel_hi:[1,0]
	v_pk_mul_f32 v[6:7], v[54:55], v[2:3] op_sel_hi:[1,0]
	v_pk_fma_f32 v[30:31], v[56:57], v[0:1], v[4:5] op_sel_hi:[1,0,1] neg_lo:[0,0,1] neg_hi:[0,0,1]
	v_pk_fma_f32 v[26:27], v[58:59], v[0:1], v[6:7] op_sel_hi:[1,0,1] neg_lo:[0,0,1] neg_hi:[0,0,1]
	v_fmac_f32_e32 v3, v30, v30
	v_fmac_f32_e32 v3, v31, v31
	v_fmac_f32_e32 v3, v26, v26
	v_fmac_f32_e32 v3, v27, v27
	v_pk_mul_f32 v[4:5], v[68:69], v[2:3] op_sel_hi:[1,0]
	v_pk_mul_f32 v[6:7], v[70:71], v[2:3] op_sel_hi:[1,0]
	v_pk_fma_f32 v[28:29], v[72:73], v[0:1], v[4:5] op_sel_hi:[1,0,1] neg_lo:[0,0,1] neg_hi:[0,0,1]
	v_pk_fma_f32 v[22:23], v[74:75], v[0:1], v[6:7] op_sel_hi:[1,0,1] neg_lo:[0,0,1] neg_hi:[0,0,1]
	v_fmac_f32_e32 v3, v28, v28
	v_fmac_f32_e32 v3, v29, v29
	v_fmac_f32_e32 v3, v22, v22
	v_fmac_f32_e32 v3, v23, v23
	v_pk_mul_f32 v[4:5], v[76:77], v[2:3] op_sel_hi:[1,0]
	v_pk_mul_f32 v[6:7], v[78:79], v[2:3] op_sel_hi:[1,0]
	v_pk_fma_f32 v[24:25], v[80:81], v[0:1], v[4:5] op_sel_hi:[1,0,1] neg_lo:[0,0,1] neg_hi:[0,0,1]
	v_pk_fma_f32 v[16:17], v[82:83], v[0:1], v[6:7] op_sel_hi:[1,0,1] neg_lo:[0,0,1] neg_hi:[0,0,1]
	v_fmac_f32_e32 v3, v24, v24
	v_fmac_f32_e32 v3, v25, v25
	v_fmac_f32_e32 v3, v16, v16
	v_fmac_f32_e32 v3, v17, v17
	v_pk_mul_f32 v[4:5], v[84:85], v[2:3] op_sel_hi:[1,0]
	v_pk_mul_f32 v[6:7], v[86:87], v[2:3] op_sel_hi:[1,0]
	v_pk_fma_f32 v[18:19], v[88:89], v[0:1], v[4:5] op_sel_hi:[1,0,1] neg_lo:[0,0,1] neg_hi:[0,0,1]
	v_pk_fma_f32 v[12:13], v[90:91], v[0:1], v[6:7] op_sel_hi:[1,0,1] neg_lo:[0,0,1] neg_hi:[0,0,1]
	v_fmac_f32_e32 v3, v18, v18
	v_fmac_f32_e32 v3, v19, v19
	v_fmac_f32_e32 v3, v12, v12
	v_fmac_f32_e32 v3, v13, v13
	v_pk_mul_f32 v[4:5], v[100:101], v[2:3] op_sel_hi:[1,0]
	v_pk_mul_f32 v[6:7], v[102:103], v[2:3] op_sel_hi:[1,0]
	v_pk_fma_f32 v[14:15], v[104:105], v[0:1], v[4:5] op_sel_hi:[1,0,1] neg_lo:[0,0,1] neg_hi:[0,0,1]
	v_pk_fma_f32 v[10:11], v[106:107], v[0:1], v[6:7] op_sel_hi:[1,0,1] neg_lo:[0,0,1] neg_hi:[0,0,1]
	v_fmac_f32_e32 v3, v14, v14
	v_fmac_f32_e32 v3, v15, v15
	v_fmac_f32_e32 v3, v10, v10
	v_fmac_f32_e32 v3, v11, v11
	v_pk_mul_f32 v[6:7], v[108:109], v[2:3] op_sel_hi:[1,0]
	v_pk_mul_f32 v[4:5], v[110:111], v[2:3] op_sel_hi:[1,0]
	v_pk_fma_f32 v[8:9], v[112:113], v[0:1], v[6:7] op_sel_hi:[1,0,1] neg_lo:[0,0,1] neg_hi:[0,0,1]
	v_pk_fma_f32 v[6:7], v[114:115], v[0:1], v[4:5] op_sel_hi:[1,0,1] neg_lo:[0,0,1] neg_hi:[0,0,1]
	v_pk_mul_f32 v[32:33], v[8:9], v[8:9]
	v_pk_mul_f32 v[4:5], v[6:7], v[6:7]
	v_add_f32_e32 v3, v32, v3
	v_add_f32_e32 v3, v33, v3
	v_add_f32_e32 v3, v4, v3
	v_add_f32_e32 v21, v5, v3
	v_pk_mul_f32 v[32:33], v[98:99], v[2:3] op_sel_hi:[1,0]
	v_pk_mul_f32 v[2:3], v[96:97], v[2:3] op_sel_hi:[1,0]
	s_nop 0
	v_pk_fma_f32 v[4:5], v[92:93], v[0:1], v[2:3] op_sel_hi:[1,0,1] neg_lo:[0,0,1] neg_hi:[0,0,1]
	v_pk_fma_f32 v[2:3], v[94:95], v[0:1], v[32:33] op_sel_hi:[1,0,1] neg_lo:[0,0,1] neg_hi:[0,0,1]
	v_pk_mul_f32 v[38:39], v[4:5], v[4:5]
	v_pk_mul_f32 v[32:33], v[2:3], v[2:3]
	v_add_f32_e32 v0, v38, v21
	v_add_f32_e32 v0, v39, v0
	v_add_f32_e32 v0, v32, v0
	v_add_f32_e32 v0, v33, v0
	ds_bpermute_b32 v21, v236, v0
	v_and_or_b32 v32, v165, 15, v167
	v_ashrrev_i32_e32 v33, 31, v32
	v_lshlrev_b64 v[32:33], 10, v[32:33]
	v_lshl_add_u64 v[32:33], s[0:1], 0, v[32:33]
	s_waitcnt lgkmcnt(0)
	v_add_f32_e32 v0, v0, v21
	ds_bpermute_b32 v21, v231, v0
	v_lshl_add_u64 v[32:33], v[32:33], 0, s[64:65]
	s_mov_b64 s[0:1], 0x5a3e000
	s_waitcnt lgkmcnt(0)
	v_add_f32_e32 v0, v0, v21
	v_fmamk_f32 v0, v0, 0x3c000000, v238
	v_cmp_gt_f32_e32 vcc, s67, v0
	v_mul_f32_e32 v21, 0x4b800000, v0
	s_nop 0
	v_cndmask_b32_e32 v0, v0, v21, vcc
	v_rsq_f32_e32 v0, v0
	s_nop 0
	v_mul_f32_e32 v21, 0x45800000, v0
	v_cndmask_b32_e32 v0, v0, v21, vcc
	v_mul_f32_e32 v20, v20, v0
	v_lshrrev_b32_e32 v0, 2, v165
	v_and_b32_e32 v21, 12, v0
	v_lshlrev_b32_e32 v0, 1, v21
	v_lshl_add_u64 v[38:39], v[32:33], 0, v[0:1]
	v_lshl_add_u64 v[32:33], v[38:39], 0, s[0:1]
	v_readlane_b32 s0, v255, 5
	v_lshlrev_b32_e32 v0, 2, v21
	v_readlane_b32 s1, v255, 6
	s_nop 4
	s_waitcnt vmcnt(0)
	v_mov_b64_e32 v[40:41], v[204:205]
	v_mov_b64_e32 v[42:43], v[206:207]
	v_pk_mul_f32 v[36:37], v[40:41], v[36:37]
	v_pk_mul_f32 v[34:35], v[42:43], v[34:35]
	s_nop 0
	v_pk_mul_f32 v[40:41], v[34:35], v[20:21] op_sel_hi:[1,0]
	v_pk_mul_f32 v[34:35], v[36:37], v[20:21] op_sel_hi:[1,0]
	v_add_co_u32_e32 v36, vcc, s70, v38
	v_cvt_pk_bf16_f32 v34, v34, v35
	v_cvt_pk_bf16_f32 v35, v40, v41
	v_addc_co_u32_e32 v37, vcc, 0, v39, vcc
	flat_store_dwordx2 v[36:37], v[34:35]
	v_mov_b64_e32 v[34:35], v[208:209]
	v_mov_b64_e32 v[36:37], v[210:211]
	v_pk_mul_f32 v[30:31], v[34:35], v[30:31]
	v_pk_mul_f32 v[26:27], v[36:37], v[26:27]
	v_pk_mul_f32 v[30:31], v[30:31], v[20:21] op_sel_hi:[1,0]
	v_pk_mul_f32 v[26:27], v[26:27], v[20:21] op_sel_hi:[1,0]
	v_cvt_pk_bf16_f32 v30, v30, v31
	v_cvt_pk_bf16_f32 v31, v26, v27
	flat_store_dwordx2 v[32:33], v[30:31] offset:32
	v_mov_b64_e32 v[34:35], v[212:213]
	v_mov_b64_e32 v[36:37], v[214:215]
	v_pk_mul_f32 v[26:27], v[28:29], v[34:35]
	v_pk_mul_f32 v[22:23], v[22:23], v[36:37]
	v_pk_mul_f32 v[26:27], v[26:27], v[20:21] op_sel_hi:[1,0]
	v_pk_mul_f32 v[22:23], v[22:23], v[20:21] op_sel_hi:[1,0]
	v_cvt_pk_bf16_f32 v26, v26, v27
	v_cvt_pk_bf16_f32 v27, v22, v23
	flat_store_dwordx2 v[32:33], v[26:27] offset:64
	v_mov_b64_e32 v[26:27], v[216:217]
	v_mov_b64_e32 v[28:29], v[218:219]
	v_pk_mul_f32 v[22:23], v[24:25], v[26:27]
	v_pk_mul_f32 v[16:17], v[16:17], v[28:29]
	v_pk_mul_f32 v[22:23], v[22:23], v[20:21] op_sel_hi:[1,0]
	v_pk_mul_f32 v[16:17], v[16:17], v[20:21] op_sel_hi:[1,0]
	v_cvt_pk_bf16_f32 v22, v22, v23
	v_cvt_pk_bf16_f32 v23, v16, v17
	flat_store_dwordx2 v[32:33], v[22:23] offset:96
	v_mov_b64_e32 v[22:23], v[220:221]
	v_mov_b64_e32 v[24:25], v[222:223]
	v_pk_mul_f32 v[16:17], v[18:19], v[22:23]
	v_pk_mul_f32 v[12:13], v[12:13], v[24:25]
	v_pk_mul_f32 v[16:17], v[16:17], v[20:21] op_sel_hi:[1,0]
	v_pk_mul_f32 v[12:13], v[12:13], v[20:21] op_sel_hi:[1,0]
	v_cvt_pk_bf16_f32 v16, v16, v17
	v_cvt_pk_bf16_f32 v17, v12, v13
	flat_store_dwordx2 v[32:33], v[16:17] offset:128
	v_mov_b64_e32 v[16:17], v[224:225]
	v_mov_b64_e32 v[18:19], v[226:227]
	v_pk_mul_f32 v[12:13], v[14:15], v[16:17]
	v_pk_mul_f32 v[10:11], v[10:11], v[18:19]
	v_pk_mul_f32 v[12:13], v[12:13], v[20:21] op_sel_hi:[1,0]
	v_pk_mul_f32 v[10:11], v[10:11], v[20:21] op_sel_hi:[1,0]
	v_cvt_pk_bf16_f32 v12, v12, v13
	v_cvt_pk_bf16_f32 v13, v10, v11
	flat_store_dwordx2 v[32:33], v[12:13] offset:160
	v_mov_b64_e32 v[10:11], v[116:117]
	v_mov_b64_e32 v[12:13], v[118:119]
	v_pk_mul_f32 v[8:9], v[8:9], v[10:11]
	v_pk_mul_f32 v[6:7], v[6:7], v[12:13]
	v_pk_mul_f32 v[8:9], v[8:9], v[20:21] op_sel_hi:[1,0]
	v_pk_mul_f32 v[6:7], v[6:7], v[20:21] op_sel_hi:[1,0]
	v_cvt_pk_bf16_f32 v8, v8, v9
	v_cvt_pk_bf16_f32 v9, v6, v7
	flat_store_dwordx2 v[32:33], v[8:9] offset:192
	v_mov_b64_e32 v[6:7], v[120:121]
	v_mov_b64_e32 v[8:9], v[122:123]
	v_pk_mul_f32 v[4:5], v[4:5], v[6:7]
	v_pk_mul_f32 v[2:3], v[2:3], v[8:9]
	v_pk_mul_f32 v[4:5], v[4:5], v[20:21] op_sel_hi:[1,0]
	v_pk_mul_f32 v[2:3], v[2:3], v[20:21] op_sel_hi:[1,0]
	v_cvt_pk_bf16_f32 v4, v4, v5
	v_cvt_pk_bf16_f32 v5, v2, v3
	flat_store_dwordx2 v[32:33], v[4:5] offset:224

.LBB0_515:
	v_readlane_b32 s0, v255, 5
	v_readlane_b32 s1, v255, 6
	v_lshrrev_b32_e32 v202, 2, v149
	v_and_b32_e32 v202, 12, v202
	v_lshlrev_b32_e32 v202, 2, v202
	s_nop 2
	global_load_dwordx4 v[204:207], v202, s[0:1]
	global_load_dwordx4 v[208:211], v202, s[0:1] offset:64
	global_load_dwordx4 v[212:215], v202, s[0:1] offset:128
	global_load_dwordx4 v[216:219], v202, s[0:1] offset:192
	global_load_dwordx4 v[220:223], v202, s[0:1] offset:256
	global_load_dwordx4 v[224:227], v202, s[0:1] offset:320
	global_load_dwordx4 v[116:119], v202, s[0:1] offset:384
	global_load_dwordx4 v[120:123], v202, s[0:1] offset:448
	ds_bpermute_b32 v2, v236, v3
	v_and_b32_e32 v0, 63, v149
	v_readlane_b32 s0, v255, 1
	v_lshlrev_b32_e32 v0, 2, v0
	v_readlane_b32 s1, v255, 2
	s_waitcnt lgkmcnt(0)
	v_add_f32_e32 v2, v3, v2
	ds_bpermute_b32 v3, v231, v2
	s_mov_b32 s2, 0x42b17218
	s_waitcnt lgkmcnt(0)
	v_add_f32_e32 v4, v2, v3
	ds_bpermute_b32 v2, v236, v184
	s_waitcnt lgkmcnt(0)
	v_add_f32_e32 v3, v184, v2
	global_load_dword v2, v0, s[0:1]
	global_load_dword v5, v0, s[0:1] offset:256
	global_load_dword v124, v0, s[0:1] offset:512
	global_load_dword v125, v0, s[0:1] offset:768
	s_waitcnt vmcnt(0)
	ds_bpermute_b32 v21, v231, v3
	v_mul_f32_e32 v6, v2, v5
	ds_bpermute_b32 v6, v231, v6
	s_waitcnt lgkmcnt(0)
	v_fmac_f32_e32 v6, v2, v5
	ds_bpermute_b32 v2, v236, v6
	s_waitcnt lgkmcnt(0)
	v_add_f32_e32 v2, v6, v2
	ds_bpermute_b32 v5, v232, v2
	s_waitcnt lgkmcnt(0)
	v_add_f32_e32 v2, v2, v5
	ds_bpermute_b32 v5, v233, v2
	s_waitcnt lgkmcnt(0)
	v_add_f32_e32 v2, v2, v5
	ds_bpermute_b32 v5, v234, v2
	s_waitcnt lgkmcnt(0)
	v_add_f32_e32 v2, v2, v5
	ds_bpermute_b32 v5, v235, v2
	s_waitcnt lgkmcnt(0)
	v_add_f32_e32 v2, v2, v5
	v_mov_b32_e32 v5, v124
	s_nop 0
	v_mov_b32_e32 v0, v125
	v_readlane_b32 s0, v255, 3
	v_readlane_b32 s1, v255, 4
	s_load_dword s0, s[0:1], 0xf8
	s_mov_b32 s1, 0xc2ce8ed0
	v_cmp_ngt_f32_e32 vcc, s1, v2
	s_mov_b32 s64, 0
	s_waitcnt lgkmcnt(0)
	v_mov_b32_e32 v20, s0
	s_waitcnt vmcnt(0)
	v_mul_f32_e32 v6, v5, v0
	ds_bpermute_b32 v6, v231, v6
	s_waitcnt lgkmcnt(0)
	v_fmac_f32_e32 v6, v5, v0
	ds_bpermute_b32 v0, v236, v6
	s_waitcnt lgkmcnt(0)
	v_add_f32_e32 v0, v6, v0
	ds_bpermute_b32 v5, v232, v0
	s_waitcnt lgkmcnt(0)
	v_add_f32_e32 v0, v0, v5
	ds_bpermute_b32 v5, v233, v0
	s_waitcnt lgkmcnt(0)
	v_add_f32_e32 v0, v0, v5
	ds_bpermute_b32 v5, v234, v0
	s_waitcnt lgkmcnt(0)
	v_add_f32_e32 v0, v0, v5
	ds_bpermute_b32 v5, v235, v0
	s_waitcnt lgkmcnt(0)
	v_add_f32_e32 v0, v0, v5
	v_mul_f32_e32 v5, 0x3fb8aa3b, v2
	v_fma_f32 v6, v2, s33, -v5
	v_rndne_f32_e32 v7, v5
	v_fmac_f32_e32 v6, 0x32a5705f, v2
	v_sub_f32_e32 v5, v5, v7
	v_add_f32_e32 v5, v5, v6
	v_exp_f32_e32 v5, v5
	v_cvt_i32_f32_e32 v6, v7
	v_ldexp_f32 v5, v5, v6
	v_cndmask_b32_e32 v5, 0, v5, vcc
	v_cmp_nlt_f32_e32 vcc, s2, v2
	s_nop 1
	v_cndmask_b32_e32 v2, v243, v5, vcc
	v_mul_f32_e32 v5, 0x3fb8aa3b, v0
	v_fma_f32 v6, v0, s33, -v5
	v_rndne_f32_e32 v7, v5
	v_fmac_f32_e32 v6, 0x32a5705f, v0
	v_sub_f32_e32 v5, v5, v7
	v_add_f32_e32 v5, v5, v6
	v_exp_f32_e32 v5, v5
	v_cvt_i32_f32_e32 v6, v7
	v_cmp_ngt_f32_e32 vcc, s1, v0
	v_ldexp_f32 v5, v5, v6
	s_nop 0
	v_cndmask_b32_e32 v5, 0, v5, vcc
	v_cmp_nlt_f32_e32 vcc, s2, v0
	s_nop 1
	v_cndmask_b32_e32 v0, v243, v5, vcc
	v_sub_f32_e32 v2, v2, v0
	v_div_scale_f32 v0, s[0:1], v4, v4, 1.0
	v_rcp_f32_e32 v5, v0
	v_pk_add_f32 v[2:3], v[20:21], v[2:3]
	v_sub_f32_e32 v20, 1.0, v20
	v_fma_f32 v6, -v0, v5, 1.0
	v_fmac_f32_e32 v5, v6, v5
	v_div_scale_f32 v6, vcc, 1.0, v4, 1.0
	v_mul_f32_e32 v7, v6, v5
	v_fma_f32 v8, -v0, v7, v6
	v_fmac_f32_e32 v7, v8, v5
	v_fma_f32 v0, -v0, v7, v6
	v_div_fmas_f32 v0, v0, v5, v7
	v_div_fixup_f32 v0, v0, v4, 1.0
	v_div_scale_f32 v4, s[0:1], v3, v3, v2
	v_rcp_f32_e32 v5, v4
	s_xor_b64 s[0:1], s[64:65], s[62:63]
	s_lshl_b32 s64, s14, 1
	v_fma_f32 v6, -v4, v5, 1.0
	v_fmac_f32_e32 v5, v6, v5
	v_div_scale_f32 v6, vcc, v2, v3, v2
	v_mul_f32_e32 v7, v6, v5
	v_fma_f32 v8, -v4, v7, v6
	v_fmac_f32_e32 v7, v8, v5
	v_fma_f32 v4, -v4, v7, v6
	v_div_fmas_f32 v4, v4, v5, v7
	v_div_fixup_f32 v2, v4, v3, v2
	v_pk_mul_f32 v[4:5], v[60:61], v[2:3] op_sel_hi:[1,0]
	v_pk_mul_f32 v[6:7], v[62:63], v[2:3] op_sel_hi:[1,0]
	v_pk_fma_f32 v[36:37], v[64:65], v[0:1], v[4:5] op_sel_hi:[1,0,1] neg_lo:[0,0,1] neg_hi:[0,0,1]
	v_pk_fma_f32 v[34:35], v[66:67], v[0:1], v[6:7] op_sel_hi:[1,0,1] neg_lo:[0,0,1] neg_hi:[0,0,1]
	v_mul_f32_e32 v3, v37, v37
	v_fmac_f32_e32 v3, v36, v36
	v_fmac_f32_e32 v3, v34, v34
	v_fmac_f32_e32 v3, v35, v35
	v_pk_mul_f32 v[4:5], v[52:53], v[2:3] op_sel_hi:[1,0]
	v_pk_mul_f32 v[6:7], v[54:55], v[2:3] op_sel_hi:[1,0]
	v_pk_fma_f32 v[30:31], v[56:57], v[0:1], v[4:5] op_sel_hi:[1,0,1] neg_lo:[0,0,1] neg_hi:[0,0,1]
	v_pk_fma_f32 v[26:27], v[58:59], v[0:1], v[6:7] op_sel_hi:[1,0,1] neg_lo:[0,0,1] neg_hi:[0,0,1]
	v_fmac_f32_e32 v3, v30, v30
	v_fmac_f32_e32 v3, v31, v31
	v_fmac_f32_e32 v3, v26, v26
	v_fmac_f32_e32 v3, v27, v27
	v_pk_mul_f32 v[4:5], v[68:69], v[2:3] op_sel_hi:[1,0]
	v_pk_mul_f32 v[6:7], v[70:71], v[2:3] op_sel_hi:[1,0]
	v_pk_fma_f32 v[28:29], v[72:73], v[0:1], v[4:5] op_sel_hi:[1,0,1] neg_lo:[0,0,1] neg_hi:[0,0,1]
	v_pk_fma_f32 v[22:23], v[74:75], v[0:1], v[6:7] op_sel_hi:[1,0,1] neg_lo:[0,0,1] neg_hi:[0,0,1]
	v_fmac_f32_e32 v3, v28, v28
	v_fmac_f32_e32 v3, v29, v29
	v_fmac_f32_e32 v3, v22, v22
	v_fmac_f32_e32 v3, v23, v23
	v_pk_mul_f32 v[4:5], v[76:77], v[2:3] op_sel_hi:[1,0]
	v_pk_mul_f32 v[6:7], v[78:79], v[2:3] op_sel_hi:[1,0]
	v_pk_fma_f32 v[24:25], v[80:81], v[0:1], v[4:5] op_sel_hi:[1,0,1] neg_lo:[0,0,1] neg_hi:[0,0,1]
	v_pk_fma_f32 v[16:17], v[82:83], v[0:1], v[6:7] op_sel_hi:[1,0,1] neg_lo:[0,0,1] neg_hi:[0,0,1]
	v_fmac_f32_e32 v3, v24, v24
	v_fmac_f32_e32 v3, v25, v25
	v_fmac_f32_e32 v3, v16, v16
	v_fmac_f32_e32 v3, v17, v17
	v_pk_mul_f32 v[4:5], v[84:85], v[2:3] op_sel_hi:[1,0]
	v_pk_mul_f32 v[6:7], v[86:87], v[2:3] op_sel_hi:[1,0]
	v_pk_fma_f32 v[18:19], v[88:89], v[0:1], v[4:5] op_sel_hi:[1,0,1] neg_lo:[0,0,1] neg_hi:[0,0,1]
	v_pk_fma_f32 v[12:13], v[90:91], v[0:1], v[6:7] op_sel_hi:[1,0,1] neg_lo:[0,0,1] neg_hi:[0,0,1]
	v_fmac_f32_e32 v3, v18, v18
	v_fmac_f32_e32 v3, v19, v19
	v_fmac_f32_e32 v3, v12, v12
	v_fmac_f32_e32 v3, v13, v13
	v_pk_mul_f32 v[4:5], v[92:93], v[2:3] op_sel_hi:[1,0]
	v_pk_mul_f32 v[6:7], v[94:95], v[2:3] op_sel_hi:[1,0]
	v_pk_fma_f32 v[14:15], v[96:97], v[0:1], v[4:5] op_sel_hi:[1,0,1] neg_lo:[0,0,1] neg_hi:[0,0,1]
	v_pk_fma_f32 v[10:11], v[98:99], v[0:1], v[6:7] op_sel_hi:[1,0,1] neg_lo:[0,0,1] neg_hi:[0,0,1]
	v_fmac_f32_e32 v3, v14, v14
	v_fmac_f32_e32 v3, v15, v15
	v_fmac_f32_e32 v3, v10, v10
	v_fmac_f32_e32 v3, v11, v11
	v_pk_mul_f32 v[6:7], v[100:101], v[2:3] op_sel_hi:[1,0]
	v_pk_mul_f32 v[4:5], v[102:103], v[2:3] op_sel_hi:[1,0]
	v_pk_fma_f32 v[8:9], v[104:105], v[0:1], v[6:7] op_sel_hi:[1,0,1] neg_lo:[0,0,1] neg_hi:[0,0,1]
	v_pk_fma_f32 v[6:7], v[106:107], v[0:1], v[4:5] op_sel_hi:[1,0,1] neg_lo:[0,0,1] neg_hi:[0,0,1]
	v_pk_mul_f32 v[32:33], v[8:9], v[8:9]
	v_pk_mul_f32 v[4:5], v[6:7], v[6:7]
	v_add_f32_e32 v3, v32, v3
	v_add_f32_e32 v3, v33, v3
	v_add_f32_e32 v3, v4, v3
	v_add_f32_e32 v21, v5, v3
	v_pk_mul_f32 v[32:33], v[110:111], v[2:3] op_sel_hi:[1,0]
	v_pk_mul_f32 v[2:3], v[108:109], v[2:3] op_sel_hi:[1,0]
	s_nop 0
	v_pk_fma_f32 v[4:5], v[112:113], v[0:1], v[2:3] op_sel_hi:[1,0,1] neg_lo:[0,0,1] neg_hi:[0,0,1]
	v_pk_fma_f32 v[2:3], v[114:115], v[0:1], v[32:33] op_sel_hi:[1,0,1] neg_lo:[0,0,1] neg_hi:[0,0,1]
	v_pk_mul_f32 v[38:39], v[4:5], v[4:5]
	v_pk_mul_f32 v[32:33], v[2:3], v[2:3]
	v_add_f32_e32 v0, v38, v21
	v_add_f32_e32 v0, v39, v0
	v_add_f32_e32 v0, v32, v0
	v_add_f32_e32 v0, v33, v0
	ds_bpermute_b32 v21, v236, v0
	v_and_or_b32 v32, v149, 15, v151
	v_ashrrev_i32_e32 v33, 31, v32
	v_lshlrev_b64 v[32:33], 10, v[32:33]
	v_lshl_add_u64 v[32:33], s[0:1], 0, v[32:33]
	s_waitcnt lgkmcnt(0)
	v_add_f32_e32 v0, v0, v21
	ds_bpermute_b32 v21, v231, v0
	v_lshl_add_u64 v[32:33], v[32:33], 0, s[64:65]
	s_mov_b64 s[0:1], 0x5a3e000
	s_waitcnt lgkmcnt(0)
	v_add_f32_e32 v0, v0, v21
	v_fmamk_f32 v0, v0, 0x3c000000, v238
	v_cmp_gt_f32_e32 vcc, s67, v0
	v_mul_f32_e32 v21, 0x4b800000, v0
	s_nop 0
	v_cndmask_b32_e32 v0, v0, v21, vcc
	v_rsq_f32_e32 v0, v0
	s_nop 0
	v_mul_f32_e32 v21, 0x45800000, v0
	v_cndmask_b32_e32 v0, v0, v21, vcc
	v_mul_f32_e32 v20, v20, v0
	v_lshrrev_b32_e32 v0, 2, v149
	v_and_b32_e32 v21, 12, v0
	v_lshlrev_b32_e32 v0, 1, v21
	v_lshl_add_u64 v[38:39], v[32:33], 0, v[0:1]
	v_lshl_add_u64 v[32:33], v[38:39], 0, s[0:1]
	v_readlane_b32 s0, v255, 5
	v_lshlrev_b32_e32 v0, 2, v21
	v_readlane_b32 s1, v255, 6
	s_nop 4
	s_waitcnt vmcnt(0)
	v_mov_b64_e32 v[40:41], v[204:205]
	v_mov_b64_e32 v[42:43], v[206:207]
	v_pk_mul_f32 v[36:37], v[40:41], v[36:37]
	v_pk_mul_f32 v[34:35], v[42:43], v[34:35]
	s_nop 0
	v_pk_mul_f32 v[40:41], v[34:35], v[20:21] op_sel_hi:[1,0]
	v_pk_mul_f32 v[34:35], v[36:37], v[20:21] op_sel_hi:[1,0]
	v_add_co_u32_e32 v36, vcc, s70, v38
	v_cvt_pk_bf16_f32 v34, v34, v35
	v_cvt_pk_bf16_f32 v35, v40, v41
	v_addc_co_u32_e32 v37, vcc, 0, v39, vcc
	flat_store_dwordx2 v[36:37], v[34:35]
	v_mov_b64_e32 v[34:35], v[208:209]
	v_mov_b64_e32 v[36:37], v[210:211]
	v_pk_mul_f32 v[30:31], v[34:35], v[30:31]
	v_pk_mul_f32 v[26:27], v[36:37], v[26:27]
	v_pk_mul_f32 v[30:31], v[30:31], v[20:21] op_sel_hi:[1,0]
	v_pk_mul_f32 v[26:27], v[26:27], v[20:21] op_sel_hi:[1,0]
	v_cvt_pk_bf16_f32 v30, v30, v31
	v_cvt_pk_bf16_f32 v31, v26, v27
	flat_store_dwordx2 v[32:33], v[30:31] offset:32
	v_mov_b64_e32 v[34:35], v[212:213]
	v_mov_b64_e32 v[36:37], v[214:215]
	v_pk_mul_f32 v[26:27], v[28:29], v[34:35]
	v_pk_mul_f32 v[22:23], v[22:23], v[36:37]
	v_pk_mul_f32 v[26:27], v[26:27], v[20:21] op_sel_hi:[1,0]
	v_pk_mul_f32 v[22:23], v[22:23], v[20:21] op_sel_hi:[1,0]
	v_cvt_pk_bf16_f32 v26, v26, v27
	v_cvt_pk_bf16_f32 v27, v22, v23
	flat_store_dwordx2 v[32:33], v[26:27] offset:64
	v_mov_b64_e32 v[26:27], v[216:217]
	v_mov_b64_e32 v[28:29], v[218:219]
	v_pk_mul_f32 v[22:23], v[24:25], v[26:27]
	v_pk_mul_f32 v[16:17], v[16:17], v[28:29]
	v_pk_mul_f32 v[22:23], v[22:23], v[20:21] op_sel_hi:[1,0]
	v_pk_mul_f32 v[16:17], v[16:17], v[20:21] op_sel_hi:[1,0]
	v_cvt_pk_bf16_f32 v22, v22, v23
	v_cvt_pk_bf16_f32 v23, v16, v17
	flat_store_dwordx2 v[32:33], v[22:23] offset:96
	v_mov_b64_e32 v[22:23], v[220:221]
	v_mov_b64_e32 v[24:25], v[222:223]
	v_pk_mul_f32 v[16:17], v[18:19], v[22:23]
	v_pk_mul_f32 v[12:13], v[12:13], v[24:25]
	v_pk_mul_f32 v[16:17], v[16:17], v[20:21] op_sel_hi:[1,0]
	v_pk_mul_f32 v[12:13], v[12:13], v[20:21] op_sel_hi:[1,0]
	v_cvt_pk_bf16_f32 v16, v16, v17
	v_cvt_pk_bf16_f32 v17, v12, v13
	flat_store_dwordx2 v[32:33], v[16:17] offset:128
	v_mov_b64_e32 v[16:17], v[224:225]
	v_mov_b64_e32 v[18:19], v[226:227]
	v_pk_mul_f32 v[12:13], v[14:15], v[16:17]
	v_pk_mul_f32 v[10:11], v[10:11], v[18:19]
	v_pk_mul_f32 v[12:13], v[12:13], v[20:21] op_sel_hi:[1,0]
	v_pk_mul_f32 v[10:11], v[10:11], v[20:21] op_sel_hi:[1,0]
	v_cvt_pk_bf16_f32 v12, v12, v13
	v_cvt_pk_bf16_f32 v13, v10, v11
	flat_store_dwordx2 v[32:33], v[12:13] offset:160
	v_mov_b64_e32 v[10:11], v[116:117]
	v_mov_b64_e32 v[12:13], v[118:119]
	v_pk_mul_f32 v[8:9], v[8:9], v[10:11]
	v_pk_mul_f32 v[6:7], v[6:7], v[12:13]
	v_pk_mul_f32 v[8:9], v[8:9], v[20:21] op_sel_hi:[1,0]
	v_pk_mul_f32 v[6:7], v[6:7], v[20:21] op_sel_hi:[1,0]
	v_cvt_pk_bf16_f32 v8, v8, v9
	v_cvt_pk_bf16_f32 v9, v6, v7
	flat_store_dwordx2 v[32:33], v[8:9] offset:192
	v_mov_b64_e32 v[6:7], v[120:121]
	v_mov_b64_e32 v[8:9], v[122:123]
	v_pk_mul_f32 v[4:5], v[4:5], v[6:7]
	v_pk_mul_f32 v[2:3], v[2:3], v[8:9]
	v_pk_mul_f32 v[4:5], v[4:5], v[20:21] op_sel_hi:[1,0]
	v_pk_mul_f32 v[2:3], v[2:3], v[20:21] op_sel_hi:[1,0]
	v_cvt_pk_bf16_f32 v4, v4, v5
	v_cvt_pk_bf16_f32 v5, v2, v3
	flat_store_dwordx2 v[32:33], v[4:5] offset:224
